# prep conv stage: interior rows (always inside the sequence) load without exec masking or zero-init
# speedup vs baseline: 1.0002x; 1.0002x over previous
.LBB0_560:
	s_or_b64 exec, exec, s[22:23]
	v_add_u32_e32 v8, v4, v168
	v_cmp_gt_u32_e64 s[50:51], s16, v8
	v_mov_b32_e32 v9, v1
	v_lshl_add_u64 v[10:11], v[8:9], 0, v[26:27]
	v_mad_u64_u32 v[12:13], s[24:25], v10, s29, v[2:3]
	v_mad_i32_i24 v13, v11, s29, v13
	global_load_dwordx4 v[142:145], v[12:13], off
.LBB0_562:
	v_add_u32_e32 v14, 2, v6
	v_cmp_gt_u32_e64 s[52:53], s16, v14
	v_mov_b32_e32 v15, v1
	v_lshl_add_u64 v[10:11], v[14:15], 0, v[26:27]
	v_mad_u64_u32 v[12:13], s[24:25], v10, s29, v[2:3]
	v_mad_i32_i24 v13, v11, s29, v13
	global_load_dwordx4 v[138:141], v[12:13], off
.LBB0_564:
	v_add_u32_e32 v16, 3, v6
	v_cmp_gt_u32_e64 s[54:55], s16, v16
	v_mov_b32_e32 v17, v1
	v_lshl_add_u64 v[10:11], v[16:17], 0, v[26:27]
	v_mad_u64_u32 v[12:13], s[24:25], v10, s29, v[2:3]
	v_mad_i32_i24 v13, v11, s29, v13
	global_load_dwordx4 v[134:137], v[12:13], off
.LBB0_566:
	v_add_u32_e32 v22, 4, v6
	v_cmp_gt_u32_e64 s[56:57], s16, v22
	v_mov_b32_e32 v23, v1
	v_lshl_add_u64 v[10:11], v[22:23], 0, v[26:27]
	v_mad_u64_u32 v[12:13], s[24:25], v10, s29, v[2:3]
	v_mad_i32_i24 v13, v11, s29, v13
	global_load_dwordx4 v[106:109], v[12:13], off
.LBB0_568:
	v_add_u32_e32 v28, 5, v6
	v_cmp_gt_u32_e64 s[58:59], s16, v28
	v_mov_b32_e32 v82, 0
	v_mov_b32_e32 v98, 0
	v_mov_b32_e32 v99, 0
	v_mov_b32_e32 v100, 0
	v_mov_b32_e32 v101, 0
	s_and_saveexec_b64 s[22:23], s[58:59]
	s_cbranch_execz .LBB0_570
	v_mov_b32_e32 v29, v1
	v_lshl_add_u64 v[10:11], v[28:29], 0, v[26:27]
	v_mad_u64_u32 v[2:3], s[24:25], v10, s29, v[2:3]
	v_mad_i32_i24 v3, v11, s29, v3
	global_load_dwordx4 v[98:101], v[2:3], off

.LBB0_572:
	s_or_b64 exec, exec, s[22:23]
	v_mov_b32_e32 v9, v1
	v_lshl_add_u64 v[10:11], v[8:9], 0, v[26:27]
	v_mov_b64_e32 v[12:13], s[38:39]
	v_mad_u64_u32 v[12:13], s[24:25], v10, s29, v[12:13]
	v_mad_i32_i24 v13, v11, s29, v13
	v_lshl_add_u64 v[10:11], v[12:13], 0, v[0:1]
	global_load_dwordx4 v[94:97], v[10:11], off
.LBB0_574:
	v_mov_b32_e32 v15, v1
	v_lshl_add_u64 v[10:11], v[14:15], 0, v[26:27]
	v_mov_b64_e32 v[12:13], s[38:39]
	v_mad_u64_u32 v[12:13], s[24:25], v10, s29, v[12:13]
	v_mad_i32_i24 v13, v11, s29, v13
	v_lshl_add_u64 v[10:11], v[12:13], 0, v[0:1]
	global_load_dwordx4 v[90:93], v[10:11], off
.LBB0_576:
	v_mov_b32_e32 v17, v1
	v_lshl_add_u64 v[10:11], v[16:17], 0, v[26:27]
	v_mov_b64_e32 v[12:13], s[38:39]
	v_mad_u64_u32 v[12:13], s[24:25], v10, s29, v[12:13]
	v_mad_i32_i24 v13, v11, s29, v13
	v_lshl_add_u64 v[10:11], v[12:13], 0, v[0:1]
	global_load_dwordx4 v[86:89], v[10:11], off
.LBB0_578:
	v_mov_b32_e32 v23, v1
	v_lshl_add_u64 v[10:11], v[22:23], 0, v[26:27]
	v_mov_b64_e32 v[12:13], s[38:39]
	v_mad_u64_u32 v[12:13], s[24:25], v10, s29, v[12:13]
	v_mad_i32_i24 v13, v11, s29, v13
	v_lshl_add_u64 v[10:11], v[12:13], 0, v[0:1]
	global_load_dwordx4 v[54:57], v[10:11], off
.LBB0_580:
	v_mov_b32_e32 v2, 0
	v_mov_b32_e32 v50, 0
	v_mov_b32_e32 v51, 0
	v_mov_b32_e32 v52, 0
	v_mov_b32_e32 v53, 0
	s_and_saveexec_b64 s[22:23], s[58:59]
	s_cbranch_execz .LBB0_582
	v_mov_b32_e32 v29, v1
	v_lshl_add_u64 v[10:11], v[28:29], 0, v[26:27]
	v_mov_b64_e32 v[12:13], s[38:39]
	v_mad_u64_u32 v[12:13], s[24:25], v10, s29, v[12:13]
	v_mad_i32_i24 v13, v11, s29, v13
	v_lshl_add_u64 v[10:11], v[12:13], 0, v[0:1]
	global_load_dwordx4 v[50:53], v[10:11], off

.LBB0_584:
	s_or_b64 exec, exec, s[22:23]
	v_mov_b32_e32 v9, v1
	v_lshl_add_u64 v[8:9], v[8:9], 0, v[26:27]
	v_mad_u64_u32 v[10:11], s[22:23], v8, s29, v[30:31]
	v_mad_i32_i24 v11, v9, s29, v11
	global_load_dwordx4 v[10:13], v[10:11], off
.LBB0_586:
	s_mov_b64 s[24:25], 0x3000
	v_mov_b32_e32 v15, v1
	v_lshl_add_u64 v[6:7], v[14:15], 0, v[26:27]
	v_mad_u64_u32 v[8:9], s[22:23], v6, s29, v[30:31]
	v_mad_i32_i24 v9, v7, s29, v9
	global_load_dwordx4 v[6:9], v[8:9], off
.LBB0_588:
	v_mov_b32_e32 v17, v1
	v_lshl_add_u64 v[16:17], v[16:17], 0, v[26:27]
	v_mad_u64_u32 v[18:19], s[22:23], v16, s29, v[30:31]
	v_mad_i32_i24 v19, v17, s29, v19
	global_load_dwordx4 v[18:21], v[18:19], off
.LBB0_590:
	v_mov_b32_e32 v23, v1
	v_lshl_add_u64 v[14:15], v[22:23], 0, v[26:27]
	v_mad_u64_u32 v[16:17], s[22:23], v14, s29, v[30:31]
	v_mad_i32_i24 v17, v15, s29, v17
	global_load_dwordx4 v[14:17], v[16:17], off
.LBB0_592:
	v_mov_b32_e32 v22, 0
	v_mov_b32_e32 v23, 0
	v_mov_b32_e32 v24, 0
	v_mov_b32_e32 v25, 0
	s_and_saveexec_b64 s[0:1], s[58:59]
	s_cbranch_execz .LBB0_594
	v_mov_b32_e32 v29, v1
	v_lshl_add_u64 v[22:23], v[28:29], 0, v[26:27]
	v_mad_u64_u32 v[24:25], s[22:23], v22, s29, v[30:31]
	v_mad_i32_i24 v25, v23, s29, v25
	global_load_dwordx4 v[22:25], v[24:25], off
